# NSA selected/window step 0: the 32-deep dependent row-sum add chain moved from the post-PV tail into the gaps between PV MFMA pairs (same order, bit-exact), shortening the per-step critical path
# baseline (speedup 1.0000x reference)
; DI unsigned cvtpk(float lo, float hi) { f32x2_t v = {lo, hi}; bf16x2_t b = __builtin_convertvector(v, bf16x2_t); return __builtin_bit_cast(unsigned, b); }
; #define MFMA32(a, b, c) __builtin_amdgcn_mfma_f32_32x32x16_bf16((a), (b), (c), 0, 0, 0)
; #define SBAR() __builtin_amdgcn_sched_barrier(0)
; template <int VSTR, int NDVB> DI void pv64(f32x16 (&O)[NDVB], const lds8* vp, const bf16x8 (&P)[4]) {
;   bf16x8 f[2][NDVB];
; #pragma unroll
;   for (int d = 0; d < NDVB; ++d) { const s16x4 lo = trrd(vp + d * 64), hi = trrd(vp + 8 * VSTR + d * 64); f[0][d] = __builtin_shufflevector(lo, hi, 0, 1, 2, 3, 4, 5, 6, 7); }
; #pragma unroll
;   for (int kk = 0; kk < 4; ++kk) {
;     if (kk < 3) {
; #pragma unroll
;       for (int d = 0; d < NDVB; ++d) { const s16x4 lo = trrd(vp + (16 * (kk + 1)) * VSTR + d * 64), hi = trrd(vp + (16 * (kk + 1) + 8) * VSTR + d * 64);
;         f[(kk + 1) & 1][d] = __builtin_shufflevector(lo, hi, 0, 1, 2, 3, 4, 5, 6, 7); }
;     }
;     SBAR();
;     __builtin_amdgcn_s_setprio(1);
; #pragma unroll
;     for (int d = 0; d < NDVB; ++d) O[d] = MFMA32(f[kk & 1][d], P[kk], O[d]);
;     __builtin_amdgcn_s_setprio(0);
;     SBAR();
;   }
; template <int NDVB, bool HAS_NEXT> DI void softmax_def(f32x16& sa0, f32x16& sa1, f32x16& sb0, f32x16& sb1, f32x16 (&O)[NDVB], float& muse, float& l, bool first, bf16x8 (&P)[4], bool check = true) {
;     ...
;   float sum = 0.f;
; #pragma unroll
;   for (int i = 0; i < 16; ++i) { sa0[i] = __builtin_amdgcn_exp2f(sa0[i]); sum += sa0[i]; }
; #pragma unroll
;   for (int i = 0; i < 16; ++i) { sa1[i] = __builtin_amdgcn_exp2f(sa1[i]); sum += sa1[i]; }
;   l += sum;
;   u32x4 w;
;   w.x = cvtpk(sa0[0], sa0[1]); w.y = cvtpk(sa0[2], sa0[3]); w.z = cvtpk(sa0[4], sa0[5]); w.w = cvtpk(sa0[6], sa0[7]); P[0] = __builtin_bit_cast(bf16x8, w);
;   w.x = cvtpk(sa0[8], sa0[9]); w.y = cvtpk(sa0[10], sa0[11]); w.z = cvtpk(sa0[12], sa0[13]); w.w = cvtpk(sa0[14], sa0[15]); P[1] = __builtin_bit_cast(bf16x8, w);
;   w.x = cvtpk(sa1[0], sa1[1]); w.y = cvtpk(sa1[2], sa1[3]); w.z = cvtpk(sa1[4], sa1[5]); w.w = cvtpk(sa1[6], sa1[7]); P[2] = __builtin_bit_cast(bf16x8, w);
;   w.x = cvtpk(sa1[8], sa1[9]); w.y = cvtpk(sa1[10], sa1[11]); w.z = cvtpk(sa1[12], sa1[13]); w.w = cvtpk(sa1[14], sa1[15]); P[3] = __builtin_bit_cast(bf16x8, w);
.LBB0_951:
	v_exp_f32_e32 v108, v60
	v_add_u32_e32 v60, s95, v216
	v_exp_f32_e32 v96, v48
	v_exp_f32_e32 v97, v49
	v_exp_f32_e32 v98, v50
	v_exp_f32_e32 v99, v51
	v_exp_f32_e32 v100, v52
	v_exp_f32_e32 v101, v53
	v_exp_f32_e32 v102, v54
	v_exp_f32_e32 v103, v55
	v_exp_f32_e32 v104, v56
	v_exp_f32_e32 v105, v57
	v_exp_f32_e32 v106, v58
	v_exp_f32_e32 v107, v59
	v_exp_f32_e32 v124, v44
	v_exp_f32_e32 v125, v45
	v_exp_f32_e32 v126, v46
	v_exp_f32_e32 v127, v47
	ds_read_b64_tr_b16 v[44:45], v60 offset:9216
	ds_read_b64_tr_b16 v[46:47], v60 offset:10368
	ds_read_b64_tr_b16 v[50:51], v60 offset:10432
	ds_read_b64_tr_b16 v[48:49], v60 offset:9280
	ds_read_b64_tr_b16 v[52:53], v60 offset:11520
	ds_read_b64_tr_b16 v[54:55], v60 offset:12672
	ds_read_b64_tr_b16 v[58:59], v60 offset:12736
	ds_read_b64_tr_b16 v[56:57], v60 offset:11584
	v_exp_f32_e32 v109, v61
	v_exp_f32_e32 v110, v62
	v_exp_f32_e32 v111, v63
	v_exp_f32_e32 v112, v32
	v_exp_f32_e32 v113, v33
	v_exp_f32_e32 v114, v34
	v_exp_f32_e32 v115, v35
	v_exp_f32_e32 v116, v36
	v_exp_f32_e32 v117, v37
	v_exp_f32_e32 v118, v38
	v_exp_f32_e32 v119, v39
	v_exp_f32_e32 v120, v40
	v_exp_f32_e32 v121, v41
	v_exp_f32_e32 v122, v42
	v_exp_f32_e32 v123, v43
	v_cvt_pk_bf16_f32 v32, v96, v97
	v_cvt_pk_bf16_f32 v33, v98, v99
	v_cvt_pk_bf16_f32 v34, v100, v101
	v_cvt_pk_bf16_f32 v35, v102, v103
	v_cvt_pk_bf16_f32 v36, v104, v105
	v_cvt_pk_bf16_f32 v37, v106, v107
	v_cvt_pk_bf16_f32 v38, v108, v109
	v_cvt_pk_bf16_f32 v39, v110, v111
	v_cvt_pk_bf16_f32 v40, v112, v113
	v_cvt_pk_bf16_f32 v41, v114, v115
	v_cvt_pk_bf16_f32 v42, v116, v117
	v_cvt_pk_bf16_f32 v43, v118, v119
	v_cvt_pk_bf16_f32 v140, v120, v121
	v_cvt_pk_bf16_f32 v141, v122, v123
	v_cvt_pk_bf16_f32 v142, v124, v125
	v_cvt_pk_bf16_f32 v143, v126, v127
	s_setprio 1
	s_waitcnt lgkmcnt(6)
	v_mfma_f32_32x32x16_bf16 v[0:15], v[44:47], v[32:35], v[0:15]
	s_waitcnt lgkmcnt(4)
	v_mfma_f32_32x32x16_bf16 v[16:31], v[48:51], v[32:35], v[16:31]
	s_setprio 0
	v_add_f32_e32 v234, 0, v96
	v_add_f32_e32 v234, v97, v234
	v_add_f32_e32 v234, v98, v234
	v_add_f32_e32 v234, v99, v234
	v_add_f32_e32 v234, v100, v234
	v_add_f32_e32 v234, v101, v234
	v_add_f32_e32 v234, v102, v234
	v_add_f32_e32 v234, v103, v234
	v_add_f32_e32 v234, v104, v234
	v_add_f32_e32 v234, v105, v234
	v_add_f32_e32 v234, v106, v234
	ds_read_b64_tr_b16 v[32:33], v60 offset:13824
	ds_read_b64_tr_b16 v[34:35], v60 offset:14976
	ds_read_b64_tr_b16 v[46:47], v60 offset:15040
	ds_read_b64_tr_b16 v[44:45], v60 offset:13888
	s_setprio 1
	s_waitcnt lgkmcnt(6)
	v_mfma_f32_32x32x16_bf16 v[0:15], v[52:55], v[36:39], v[0:15]
	s_waitcnt lgkmcnt(4)
	v_mfma_f32_32x32x16_bf16 v[16:31], v[56:59], v[36:39], v[16:31]
	s_setprio 0
	v_add_f32_e32 v234, v107, v234
	v_add_f32_e32 v234, v108, v234
	v_add_f32_e32 v234, v109, v234
	v_add_f32_e32 v234, v110, v234
	v_add_f32_e32 v234, v111, v234
	v_add_f32_e32 v234, v112, v234
	v_add_f32_e32 v234, v113, v234
	v_add_f32_e32 v234, v114, v234
	v_add_f32_e32 v234, v115, v234
	v_add_f32_e32 v234, v116, v234
	v_add_f32_e32 v234, v117, v234
	ds_read_b64_tr_b16 v[48:49], v60 offset:16128
	ds_read_b64_tr_b16 v[50:51], v60 offset:17280
	ds_read_b64_tr_b16 v[146:147], v60 offset:17344
	ds_read_b64_tr_b16 v[144:145], v60 offset:16192
	s_setprio 1
	s_waitcnt lgkmcnt(6)
	v_mfma_f32_32x32x16_bf16 v[0:15], v[32:35], v[40:43], v[0:15]
	s_waitcnt lgkmcnt(4)
	v_mfma_f32_32x32x16_bf16 v[16:31], v[44:47], v[40:43], v[16:31]
	s_setprio 0
	v_add_f32_e32 v234, v118, v234
	v_add_f32_e32 v234, v119, v234
	v_add_f32_e32 v234, v120, v234
	v_add_f32_e32 v234, v121, v234
	v_add_f32_e32 v234, v122, v234
	v_add_f32_e32 v234, v123, v234
	v_add_f32_e32 v234, v124, v234
	v_add_f32_e32 v234, v125, v234
	v_add_f32_e32 v234, v126, v234
	v_add_f32_e32 v234, v127, v234
	s_setprio 1
	s_waitcnt lgkmcnt(2)
	v_mfma_f32_32x32x16_bf16 v[0:15], v[48:51], v[140:143], v[0:15]
	s_waitcnt lgkmcnt(0)
	v_mfma_f32_32x32x16_bf16 v[16:31], v[144:147], v[140:143], v[16:31]
	s_setprio 0
	s_andn2_b64 vcc, exec, s[82:83]
	s_cbranch_vccnz .LBB0_953
	s_addk_i32 s94, 0xb800
	s_cmp_lg_u32 s6, 0
	s_cselect_b32 s82, s94, 0x9000
	v_add_u32_e32 v235, s82, v215
	s_waitcnt vmcnt(1)
	ds_write_b128 v235, v[128:131]
	s_waitcnt vmcnt(0)
	ds_write_b128 v235, v[132:135] offset:9216
.LBB0_953:
	s_add_i32 s86, s6, 1
	s_cmp_lg_u32 s6, 2
	s_cselect_b32 s86, s86, 0
	s_mul_i32 s86, s86, 0x4800
	v_mov_b32_e32 v140, s90
	v_add_u32_e32 v60, s86, v213
	ds_read_b32 v232, v140 offset:12
	ds_read_b32 v233, v140 offset:4
	ds_read_b128 v[32:35], v60 offset:4608
	ds_read_b128 v[36:39], v60
	ds_read_b128 v[40:43], v60 offset:32
	ds_read_b128 v[44:47], v60 offset:4640
	ds_read_b128 v[48:51], v60 offset:64
	ds_read_b128 v[52:55], v60 offset:4672
	ds_read_b128 v[56:59], v60 offset:96
	ds_read_b128 v[60:63], v60 offset:4704
	s_add_i32 s84, s89, -2
	v_add_f32_e32 v139, v219, v234
	s_mov_b64 s[82:83], -1
	s_cmp_ge_u32 s84, s88
	s_mov_b64 s[84:85], -1
	s_movk_i32 s95, 0x1ff
	s_waitcnt lgkmcnt(0)
	s_barrier
	s_cbranch_scc1 .LBB0_937
	s_cmp_lt_u32 s89, s88
	s_cselect_b64 s[82:83], -1, 0
	s_add_i32 s84, s6, 1
	s_cmp_lg_u32 s6, 2
	s_cselect_b32 s6, s84, 0
	s_mul_i32 s86, s6, 0x4800
	s_add_i32 s87, s86, 0
	s_cmp_ge_u32 s89, s88
	s_cbranch_scc1 .Lslc1_noload
	s_waitcnt lgkmcnt(9)
	v_readfirstlane_b32 s84, v232
	s_nop 1
	v_lshl_add_u32 v228, s84, 6, v212
	v_ashrrev_i32_e32 v229, 31, v228
	v_lshlrev_b64 v[228:229], 9, v[228:229]
	v_lshl_add_u64 v[230:231], v[194:195], 0, v[228:229]
	v_lshl_add_u64 v[228:229], v[196:197], 0, v[228:229]
	global_load_dwordx4 v[128:131], v[230:231], off
	global_load_dwordx4 v[132:135], v[228:229], off

; DI unsigned cvtpk(float lo, float hi) { f32x2_t v = {lo, hi}; bf16x2_t b = __builtin_convertvector(v, bf16x2_t); return __builtin_bit_cast(unsigned, b); }
; #define MFMA32(a, b, c) __builtin_amdgcn_mfma_f32_32x32x16_bf16((a), (b), (c), 0, 0, 0)
; #define SBAR() __builtin_amdgcn_sched_barrier(0)
; template <int VSTR, int NDVB> DI void pv64(f32x16 (&O)[NDVB], const lds8* vp, const bf16x8 (&P)[4]) {
;   bf16x8 f[2][NDVB];
; #pragma unroll
;   for (int d = 0; d < NDVB; ++d) { const s16x4 lo = trrd(vp + d * 64), hi = trrd(vp + 8 * VSTR + d * 64); f[0][d] = __builtin_shufflevector(lo, hi, 0, 1, 2, 3, 4, 5, 6, 7); }
; #pragma unroll
;   for (int kk = 0; kk < 4; ++kk) {
;     if (kk < 3) {
; #pragma unroll
;       for (int d = 0; d < NDVB; ++d) { const s16x4 lo = trrd(vp + (16 * (kk + 1)) * VSTR + d * 64), hi = trrd(vp + (16 * (kk + 1) + 8) * VSTR + d * 64);
;         f[(kk + 1) & 1][d] = __builtin_shufflevector(lo, hi, 0, 1, 2, 3, 4, 5, 6, 7); }
;     }
;     SBAR();
;     __builtin_amdgcn_s_setprio(1);
; #pragma unroll
;     for (int d = 0; d < NDVB; ++d) O[d] = MFMA32(f[kk & 1][d], P[kk], O[d]);
;     __builtin_amdgcn_s_setprio(0);
;     SBAR();
;   }
; template <int NDVB, bool HAS_NEXT> DI void softmax_def(f32x16& sa0, f32x16& sa1, f32x16& sb0, f32x16& sb1, f32x16 (&O)[NDVB], float& muse, float& l, bool first, bf16x8 (&P)[4], bool check = true) {
;     ...
;   float sum = 0.f;
; #pragma unroll
;   for (int i = 0; i < 16; ++i) { sa0[i] = __builtin_amdgcn_exp2f(sa0[i]); sum += sa0[i]; }
; #pragma unroll
;   for (int i = 0; i < 16; ++i) { sa1[i] = __builtin_amdgcn_exp2f(sa1[i]); sum += sa1[i]; }
;   l += sum;
;   u32x4 w;
;   w.x = cvtpk(sa0[0], sa0[1]); w.y = cvtpk(sa0[2], sa0[3]); w.z = cvtpk(sa0[4], sa0[5]); w.w = cvtpk(sa0[6], sa0[7]); P[0] = __builtin_bit_cast(bf16x8, w);
;   w.x = cvtpk(sa0[8], sa0[9]); w.y = cvtpk(sa0[10], sa0[11]); w.z = cvtpk(sa0[12], sa0[13]); w.w = cvtpk(sa0[14], sa0[15]); P[1] = __builtin_bit_cast(bf16x8, w);
;   w.x = cvtpk(sa1[0], sa1[1]); w.y = cvtpk(sa1[2], sa1[3]); w.z = cvtpk(sa1[4], sa1[5]); w.w = cvtpk(sa1[6], sa1[7]); P[2] = __builtin_bit_cast(bf16x8, w);
;   w.x = cvtpk(sa1[8], sa1[9]); w.y = cvtpk(sa1[10], sa1[11]); w.z = cvtpk(sa1[12], sa1[13]); w.w = cvtpk(sa1[14], sa1[15]); P[3] = __builtin_bit_cast(bf16x8, w);
.LBB0_994:
	v_exp_f32_e32 v141, v124
	v_add_u32_e32 v124, s49, v216
	v_exp_f32_e32 v129, v112
	v_exp_f32_e32 v130, v113
	v_exp_f32_e32 v131, v114
	v_exp_f32_e32 v132, v115
	v_exp_f32_e32 v133, v116
	v_exp_f32_e32 v134, v117
	v_exp_f32_e32 v135, v118
	v_exp_f32_e32 v136, v119
	v_exp_f32_e32 v137, v120
	v_exp_f32_e32 v138, v121
	v_exp_f32_e32 v139, v122
	v_exp_f32_e32 v140, v123
	v_exp_f32_e32 v157, v108
	v_exp_f32_e32 v158, v109
	v_exp_f32_e32 v159, v110
	v_exp_f32_e32 v222, v111
	ds_read_b64_tr_b16 v[108:109], v124 offset:9216
	ds_read_b64_tr_b16 v[110:111], v124 offset:10368
	ds_read_b64_tr_b16 v[114:115], v124 offset:10432
	ds_read_b64_tr_b16 v[112:113], v124 offset:9280
	ds_read_b64_tr_b16 v[116:117], v124 offset:11520
	ds_read_b64_tr_b16 v[118:119], v124 offset:12672
	ds_read_b64_tr_b16 v[122:123], v124 offset:12736
	ds_read_b64_tr_b16 v[120:121], v124 offset:11584
	v_exp_f32_e32 v142, v125
	v_exp_f32_e32 v143, v126
	v_exp_f32_e32 v144, v127
	v_exp_f32_e32 v145, v96
	v_exp_f32_e32 v146, v97
	v_exp_f32_e32 v147, v98
	v_exp_f32_e32 v148, v99
	v_exp_f32_e32 v149, v100
	v_exp_f32_e32 v150, v101
	v_exp_f32_e32 v151, v102
	v_exp_f32_e32 v152, v103
	v_exp_f32_e32 v153, v104
	v_exp_f32_e32 v154, v105
	v_exp_f32_e32 v155, v106
	v_exp_f32_e32 v156, v107
	v_cvt_pk_bf16_f32 v96, v129, v130
	v_cvt_pk_bf16_f32 v97, v131, v132
	v_cvt_pk_bf16_f32 v98, v133, v134
	v_cvt_pk_bf16_f32 v99, v135, v136
	v_cvt_pk_bf16_f32 v100, v137, v138
	v_cvt_pk_bf16_f32 v101, v139, v140
	v_cvt_pk_bf16_f32 v102, v141, v142
	v_cvt_pk_bf16_f32 v103, v143, v144
	v_cvt_pk_bf16_f32 v104, v145, v146
	v_cvt_pk_bf16_f32 v105, v147, v148
	v_cvt_pk_bf16_f32 v106, v149, v150
	v_cvt_pk_bf16_f32 v107, v151, v152
	v_cvt_pk_bf16_f32 v224, v153, v154
	v_cvt_pk_bf16_f32 v225, v155, v156
	v_cvt_pk_bf16_f32 v226, v157, v158
	v_cvt_pk_bf16_f32 v227, v159, v222
	s_setprio 1
	s_waitcnt lgkmcnt(6)
	v_mfma_f32_32x32x16_bf16 v[32:47], v[108:111], v[96:99], v[32:47]
	s_waitcnt lgkmcnt(4)
	v_mfma_f32_32x32x16_bf16 v[48:63], v[112:115], v[96:99], v[48:63]
	s_setprio 0
	v_add_f32_e32 v234, 0, v129
	v_add_f32_e32 v234, v130, v234
	v_add_f32_e32 v234, v131, v234
	v_add_f32_e32 v234, v132, v234
	v_add_f32_e32 v234, v133, v234
	v_add_f32_e32 v234, v134, v234
	v_add_f32_e32 v234, v135, v234
	v_add_f32_e32 v234, v136, v234
	v_add_f32_e32 v234, v137, v234
	v_add_f32_e32 v234, v138, v234
	v_add_f32_e32 v234, v139, v234
	ds_read_b64_tr_b16 v[96:97], v124 offset:13824
	ds_read_b64_tr_b16 v[98:99], v124 offset:14976
	ds_read_b64_tr_b16 v[110:111], v124 offset:15040
	ds_read_b64_tr_b16 v[108:109], v124 offset:13888
	s_setprio 1
	s_waitcnt lgkmcnt(6)
	v_mfma_f32_32x32x16_bf16 v[32:47], v[116:119], v[100:103], v[32:47]
	s_waitcnt lgkmcnt(4)
	v_mfma_f32_32x32x16_bf16 v[48:63], v[120:123], v[100:103], v[48:63]
	s_setprio 0
	v_add_f32_e32 v234, v140, v234
	v_add_f32_e32 v234, v141, v234
	v_add_f32_e32 v234, v142, v234
	v_add_f32_e32 v234, v143, v234
	v_add_f32_e32 v234, v144, v234
	v_add_f32_e32 v234, v145, v234
	v_add_f32_e32 v234, v146, v234
	v_add_f32_e32 v234, v147, v234
	v_add_f32_e32 v234, v148, v234
	v_add_f32_e32 v234, v149, v234
	v_add_f32_e32 v234, v150, v234
	ds_read_b64_tr_b16 v[112:113], v124 offset:16128
	ds_read_b64_tr_b16 v[114:115], v124 offset:17280
	ds_read_b64_tr_b16 v[230:231], v124 offset:17344
	ds_read_b64_tr_b16 v[228:229], v124 offset:16192
	s_setprio 1
	s_waitcnt lgkmcnt(6)
	v_mfma_f32_32x32x16_bf16 v[32:47], v[96:99], v[104:107], v[32:47]
	s_waitcnt lgkmcnt(4)
	v_mfma_f32_32x32x16_bf16 v[48:63], v[108:111], v[104:107], v[48:63]
	s_setprio 0
	v_add_f32_e32 v234, v151, v234
	v_add_f32_e32 v234, v152, v234
	v_add_f32_e32 v234, v153, v234
	v_add_f32_e32 v234, v154, v234
	v_add_f32_e32 v234, v155, v234
	v_add_f32_e32 v234, v156, v234
	v_add_f32_e32 v234, v157, v234
	v_add_f32_e32 v234, v158, v234
	v_add_f32_e32 v234, v159, v234
	v_add_f32_e32 v234, v222, v234
	s_setprio 1
	s_waitcnt lgkmcnt(2)
	v_mfma_f32_32x32x16_bf16 v[32:47], v[112:115], v[224:227], v[32:47]
	s_waitcnt lgkmcnt(0)
	v_mfma_f32_32x32x16_bf16 v[48:63], v[228:231], v[224:227], v[48:63]
	s_setprio 0
	s_andn2_b64 vcc, exec, s[42:43]
	s_cbranch_vccnz .LBB0_996
	s_addk_i32 s48, 0xb800
	s_cmp_lg_u32 s6, 0
	s_cselect_b32 s8, s48, 0x9000
	v_add_u32_e32 v96, s8, v215
	s_waitcnt vmcnt(1)
	ds_write_b128 v96, v[176:179]
	s_waitcnt vmcnt(0)
	ds_write_b128 v96, v[180:183] offset:9216
.LBB0_996:
	s_add_i32 s10, s46, -2
	v_add_f32_e32 v222, v128, v234
	s_mov_b64 s[8:9], -1
	s_cmp_ge_u32 s10, s3
	s_mov_b64 s[10:11], -1
	s_waitcnt lgkmcnt(0)
	s_barrier
	s_cbranch_scc1 .LBB0_980
	s_cmp_lt_u32 s46, s3
	s_cselect_b64 s[42:43], -1, 0
	s_add_i32 s8, s6, 1
	s_cmp_lg_u32 s6, 2
	s_cselect_b32 s6, s8, 0
	s_mul_i32 s48, s6, 0x4800
	s_add_i32 s49, s48, 0
	v_mov_b32_e32 v128, s0
	v_add_u32_e32 v124, s49, v213
	ds_read_b32 v128, v128 offset:12
	ds_read_b128 v[96:99], v124
	ds_read_b128 v[100:103], v124 offset:32
	ds_read_b128 v[104:107], v124 offset:4608
	ds_read_b128 v[108:111], v124 offset:4640
	ds_read_b128 v[112:115], v124 offset:64
	ds_read_b128 v[116:119], v124 offset:96
	ds_read_b128 v[120:123], v124 offset:4672
	ds_read_b128 v[124:127], v124 offset:4704
	s_cmp_ge_u32 s46, s3
	s_cbranch_scc1 .Lwin1_noload
	s_waitcnt lgkmcnt(8)
	v_readfirstlane_b32 s8, v128
	s_nop 1
	v_lshl_add_u32 v128, s8, 6, v212
	v_ashrrev_i32_e32 v129, 31, v128
	v_lshlrev_b64 v[128:129], 9, v[128:129]
	v_lshl_add_u64 v[130:131], v[194:195], 0, v[128:129]
	v_lshl_add_u64 v[128:129], v[196:197], 0, v[128:129]
	global_load_dwordx4 v[176:179], v[130:131], off offset:256
	global_load_dwordx4 v[180:183], v[128:129], off offset:256
